# v29: v26 + P2 sample-row pooling window loads issued 4 steps at a time (same accumulation order)
# baseline (speedup 1.0000x reference)
; __global__ void __launch_bounds__(512, 2) mega_fwd(Args args) {
;     ...
;             for (int j = 0; j < w; ++j) { const int e15 = 15 + tq - j; float f[8];
;                 if (e15 >= 15) unpack8(*(const u32x4*)(PROJ + (size_t)(T + b * 4 + e15 - 15) * INW + c0), f);
;                 else { const float* sp = state_pool + ((size_t)b * 15 + e15) * 1024 + c0; const f32x4 a = *(const f32x4*)sp, bb = *(const f32x4*)(sp + 4);
;                     f[0] = a.x; f[1] = a.y; f[2] = a.z; f[3] = a.w; f[4] = bb.x; f[5] = bb.y; f[6] = bb.z; f[7] = bb.w; }
; #pragma unroll
;                 for (int e = 0; e < 8; ++e) { acc[e] += f[e]; if (j == 0) cur[e] = f[e]; } }
.LBB0_318:
	s_mov_b64 s[10:11], exec
	s_load_dwordx2 s[46:47], s[8:9], 0x10
	v_mov_b32_e32 v15, v9
	s_waitcnt lgkmcnt(0)
.Lsp_chunk:
	v_add_u32_e32 v8, 0xffffc00f, v17
	v_cmp_gt_i32_e32 vcc, 15, v8
	s_and_saveexec_b64 s[20:21], vcc
	v_lshl_add_u64 v[0:1], s[6:7], 0, v[8:9]
	v_lshlrev_b64 v[0:1], 12, v[0:1]
	v_lshl_add_u64 v[0:1], s[46:47], 0, v[0:1]
	v_lshl_add_u64 v[0:1], v[0:1], 0, v[14:15]
	global_load_dwordx4 v[208:211], v[0:1], off
	global_load_dwordx4 v[212:215], v[0:1], off offset:16
	s_nop 1
	s_andn2_b64 exec, s[10:11], exec
	s_mov_b64 s[20:21], exec
	v_add_u32_e32 v0, s18, v17
	v_ashrrev_i32_e32 v1, 31, v0
	v_lshlrev_b64 v[0:1], 13, v[0:1]
	v_lshl_add_u64 v[0:1], v[10:11], 0, v[0:1]
	global_load_dwordx4 v[212:215], v[0:1], off
	s_nop 1
	s_mov_b64 exec, s[10:11]
	v_add_u32_e32 v17, -1, v17
	s_cmp_le_u32 s19, 1
	s_cbranch_scc1 .Lsp_acc1
	v_add_u32_e32 v8, 0xffffc00f, v17
	v_cmp_gt_i32_e32 vcc, 15, v8
	s_and_saveexec_b64 s[22:23], vcc
	v_lshl_add_u64 v[0:1], s[6:7], 0, v[8:9]
	v_lshlrev_b64 v[0:1], 12, v[0:1]
	v_lshl_add_u64 v[0:1], s[46:47], 0, v[0:1]
	v_lshl_add_u64 v[0:1], v[0:1], 0, v[14:15]
	global_load_dwordx4 v[216:219], v[0:1], off
	global_load_dwordx4 v[220:223], v[0:1], off offset:16
	s_nop 1
	s_andn2_b64 exec, s[10:11], exec
	s_mov_b64 s[22:23], exec
	v_add_u32_e32 v0, s18, v17
	v_ashrrev_i32_e32 v1, 31, v0
	v_lshlrev_b64 v[0:1], 13, v[0:1]
	v_lshl_add_u64 v[0:1], v[10:11], 0, v[0:1]
	global_load_dwordx4 v[220:223], v[0:1], off
	s_nop 1
	s_mov_b64 exec, s[10:11]
	v_add_u32_e32 v17, -1, v17
	s_cmp_le_u32 s19, 2
	s_cbranch_scc1 .Lsp_acc2
	v_add_u32_e32 v8, 0xffffc00f, v17
	v_cmp_gt_i32_e32 vcc, 15, v8
	s_and_saveexec_b64 s[30:31], vcc
	v_lshl_add_u64 v[0:1], s[6:7], 0, v[8:9]
	v_lshlrev_b64 v[0:1], 12, v[0:1]
	v_lshl_add_u64 v[0:1], s[46:47], 0, v[0:1]
	v_lshl_add_u64 v[0:1], v[0:1], 0, v[14:15]
	global_load_dwordx4 v[224:227], v[0:1], off
	global_load_dwordx4 v[228:231], v[0:1], off offset:16
	s_nop 1
	s_andn2_b64 exec, s[10:11], exec
	s_mov_b64 s[30:31], exec
	v_add_u32_e32 v0, s18, v17
	v_ashrrev_i32_e32 v1, 31, v0
	v_lshlrev_b64 v[0:1], 13, v[0:1]
	v_lshl_add_u64 v[0:1], v[10:11], 0, v[0:1]
	global_load_dwordx4 v[228:231], v[0:1], off
	s_nop 1
	s_mov_b64 exec, s[10:11]
	v_add_u32_e32 v17, -1, v17
	s_cmp_le_u32 s19, 3
	s_cbranch_scc1 .Lsp_acc3
	v_add_u32_e32 v8, 0xffffc00f, v17
	v_cmp_gt_i32_e32 vcc, 15, v8
	s_and_saveexec_b64 s[44:45], vcc
	v_lshl_add_u64 v[0:1], s[6:7], 0, v[8:9]
	v_lshlrev_b64 v[0:1], 12, v[0:1]
	v_lshl_add_u64 v[0:1], s[46:47], 0, v[0:1]
	v_lshl_add_u64 v[0:1], v[0:1], 0, v[14:15]
	global_load_dwordx4 v[198:201], v[0:1], off
	global_load_dwordx4 v[202:205], v[0:1], off offset:16
	s_nop 1
	s_andn2_b64 exec, s[10:11], exec
	s_mov_b64 s[44:45], exec
	v_add_u32_e32 v0, s18, v17
	v_ashrrev_i32_e32 v1, 31, v0
	v_lshlrev_b64 v[0:1], 13, v[0:1]
	v_lshl_add_u64 v[0:1], v[10:11], 0, v[0:1]
	global_load_dwordx4 v[202:205], v[0:1], off
	s_nop 1
	s_mov_b64 exec, s[10:11]
	v_add_u32_e32 v17, -1, v17
	s_waitcnt vmcnt(0)
	s_mov_b64 exec, s[20:21]
	v_lshlrev_b32_e32 v208, 16, v212
	v_and_b32_e32 v209, 0xffff0000, v212
	v_lshlrev_b32_e32 v210, 16, v213
	v_and_b32_e32 v211, 0xffff0000, v213
	v_lshlrev_b32_e32 v212, 16, v214
	v_and_b32_e32 v213, 0xffff0000, v214
	v_lshlrev_b32_e32 v214, 16, v215
	v_and_b32_e32 v215, 0xffff0000, v215
	s_mov_b64 exec, s[10:11]
	v_pk_add_f32 v[32:33], v[208:209], v[32:33]
	v_pk_add_f32 v[28:29], v[210:211], v[28:29]
	v_pk_add_f32 v[24:25], v[212:213], v[24:25]
	v_pk_add_f32 v[20:21], v[214:215], v[20:21]
	s_mov_b64 exec, s[22:23]
	v_lshlrev_b32_e32 v216, 16, v220
	v_and_b32_e32 v217, 0xffff0000, v220
	v_lshlrev_b32_e32 v218, 16, v221
	v_and_b32_e32 v219, 0xffff0000, v221
	v_lshlrev_b32_e32 v220, 16, v222
	v_and_b32_e32 v221, 0xffff0000, v222
	v_lshlrev_b32_e32 v222, 16, v223
	v_and_b32_e32 v223, 0xffff0000, v223
	s_mov_b64 exec, s[10:11]
	v_pk_add_f32 v[32:33], v[216:217], v[32:33]
	v_pk_add_f32 v[28:29], v[218:219], v[28:29]
	v_pk_add_f32 v[24:25], v[220:221], v[24:25]
	v_pk_add_f32 v[20:21], v[222:223], v[20:21]
	s_mov_b64 exec, s[30:31]
	v_lshlrev_b32_e32 v224, 16, v228
	v_and_b32_e32 v225, 0xffff0000, v228
	v_lshlrev_b32_e32 v226, 16, v229
	v_and_b32_e32 v227, 0xffff0000, v229
	v_lshlrev_b32_e32 v228, 16, v230
	v_and_b32_e32 v229, 0xffff0000, v230
	v_lshlrev_b32_e32 v230, 16, v231
	v_and_b32_e32 v231, 0xffff0000, v231
	s_mov_b64 exec, s[10:11]
	v_pk_add_f32 v[32:33], v[224:225], v[32:33]
	v_pk_add_f32 v[28:29], v[226:227], v[28:29]
	v_pk_add_f32 v[24:25], v[228:229], v[24:25]
	v_pk_add_f32 v[20:21], v[230:231], v[20:21]
	s_mov_b64 exec, s[44:45]
	v_lshlrev_b32_e32 v198, 16, v202
	v_and_b32_e32 v199, 0xffff0000, v202
	v_lshlrev_b32_e32 v200, 16, v203
	v_and_b32_e32 v201, 0xffff0000, v203
	v_lshlrev_b32_e32 v202, 16, v204
	v_and_b32_e32 v203, 0xffff0000, v204
	v_lshlrev_b32_e32 v204, 16, v205
	v_and_b32_e32 v205, 0xffff0000, v205
	s_mov_b64 exec, s[10:11]
	v_pk_add_f32 v[32:33], v[198:199], v[32:33]
	v_pk_add_f32 v[28:29], v[200:201], v[28:29]
	v_pk_add_f32 v[24:25], v[202:203], v[24:25]
	v_pk_add_f32 v[20:21], v[204:205], v[20:21]
	s_add_i32 s19, s19, -4
	s_cmp_eq_u32 s19, 0
	s_cbranch_scc1 .LBB0_315
	s_branch .Lsp_chunk
; __global__ void __launch_bounds__(512, 2) mega_fwd(Args args) {
;     ...
;             for (int j = 0; j < w; ++j) { const int e15 = 15 + tq - j; float f[8];
;                 if (e15 >= 15) unpack8(*(const u32x4*)(PROJ + (size_t)(T + b * 4 + e15 - 15) * INW + c0), f);
;                 else { const float* sp = state_pool + ((size_t)b * 15 + e15) * 1024 + c0; const f32x4 a = *(const f32x4*)sp, bb = *(const f32x4*)(sp + 4);
;                     f[0] = a.x; f[1] = a.y; f[2] = a.z; f[3] = a.w; f[4] = bb.x; f[5] = bb.y; f[6] = bb.z; f[7] = bb.w; }
; #pragma unroll
;                 for (int e = 0; e < 8; ++e) { acc[e] += f[e]; if (j == 0) cur[e] = f[e]; } }
.Lsp_acc3:
	s_waitcnt vmcnt(0)
	s_mov_b64 exec, s[20:21]
	v_lshlrev_b32_e32 v208, 16, v212
	v_and_b32_e32 v209, 0xffff0000, v212
	v_lshlrev_b32_e32 v210, 16, v213
	v_and_b32_e32 v211, 0xffff0000, v213
	v_lshlrev_b32_e32 v212, 16, v214
	v_and_b32_e32 v213, 0xffff0000, v214
	v_lshlrev_b32_e32 v214, 16, v215
	v_and_b32_e32 v215, 0xffff0000, v215
	s_mov_b64 exec, s[10:11]
	v_pk_add_f32 v[32:33], v[208:209], v[32:33]
	v_pk_add_f32 v[28:29], v[210:211], v[28:29]
	v_pk_add_f32 v[24:25], v[212:213], v[24:25]
	v_pk_add_f32 v[20:21], v[214:215], v[20:21]
	s_mov_b64 exec, s[22:23]
	v_lshlrev_b32_e32 v216, 16, v220
	v_and_b32_e32 v217, 0xffff0000, v220
	v_lshlrev_b32_e32 v218, 16, v221
	v_and_b32_e32 v219, 0xffff0000, v221
	v_lshlrev_b32_e32 v220, 16, v222
	v_and_b32_e32 v221, 0xffff0000, v222
	v_lshlrev_b32_e32 v222, 16, v223
	v_and_b32_e32 v223, 0xffff0000, v223
	s_mov_b64 exec, s[10:11]
	v_pk_add_f32 v[32:33], v[216:217], v[32:33]
	v_pk_add_f32 v[28:29], v[218:219], v[28:29]
	v_pk_add_f32 v[24:25], v[220:221], v[24:25]
	v_pk_add_f32 v[20:21], v[222:223], v[20:21]
	s_mov_b64 exec, s[30:31]
	v_lshlrev_b32_e32 v224, 16, v228
	v_and_b32_e32 v225, 0xffff0000, v228
	v_lshlrev_b32_e32 v226, 16, v229
	v_and_b32_e32 v227, 0xffff0000, v229
	v_lshlrev_b32_e32 v228, 16, v230
	v_and_b32_e32 v229, 0xffff0000, v230
	v_lshlrev_b32_e32 v230, 16, v231
	v_and_b32_e32 v231, 0xffff0000, v231
	s_mov_b64 exec, s[10:11]
	v_pk_add_f32 v[32:33], v[224:225], v[32:33]
	v_pk_add_f32 v[28:29], v[226:227], v[28:29]
	v_pk_add_f32 v[24:25], v[228:229], v[24:25]
	v_pk_add_f32 v[20:21], v[230:231], v[20:21]
	s_branch .LBB0_315
.Lsp_acc2:
	s_waitcnt vmcnt(0)
	s_mov_b64 exec, s[20:21]
	v_lshlrev_b32_e32 v208, 16, v212
	v_and_b32_e32 v209, 0xffff0000, v212
	v_lshlrev_b32_e32 v210, 16, v213
	v_and_b32_e32 v211, 0xffff0000, v213
	v_lshlrev_b32_e32 v212, 16, v214
	v_and_b32_e32 v213, 0xffff0000, v214
	v_lshlrev_b32_e32 v214, 16, v215
	v_and_b32_e32 v215, 0xffff0000, v215
	s_mov_b64 exec, s[10:11]
	v_pk_add_f32 v[32:33], v[208:209], v[32:33]
	v_pk_add_f32 v[28:29], v[210:211], v[28:29]
	v_pk_add_f32 v[24:25], v[212:213], v[24:25]
	v_pk_add_f32 v[20:21], v[214:215], v[20:21]
	s_mov_b64 exec, s[22:23]
	v_lshlrev_b32_e32 v216, 16, v220
	v_and_b32_e32 v217, 0xffff0000, v220
	v_lshlrev_b32_e32 v218, 16, v221
	v_and_b32_e32 v219, 0xffff0000, v221
	v_lshlrev_b32_e32 v220, 16, v222
	v_and_b32_e32 v221, 0xffff0000, v222
	v_lshlrev_b32_e32 v222, 16, v223
	v_and_b32_e32 v223, 0xffff0000, v223
	s_mov_b64 exec, s[10:11]
	v_pk_add_f32 v[32:33], v[216:217], v[32:33]
	v_pk_add_f32 v[28:29], v[218:219], v[28:29]
	v_pk_add_f32 v[24:25], v[220:221], v[24:25]
	v_pk_add_f32 v[20:21], v[222:223], v[20:21]
	s_branch .LBB0_315
.Lsp_acc1:
	s_waitcnt vmcnt(0)
	s_mov_b64 exec, s[20:21]
	v_lshlrev_b32_e32 v208, 16, v212
	v_and_b32_e32 v209, 0xffff0000, v212
	v_lshlrev_b32_e32 v210, 16, v213
	v_and_b32_e32 v211, 0xffff0000, v213
	v_lshlrev_b32_e32 v212, 16, v214
	v_and_b32_e32 v213, 0xffff0000, v214
	v_lshlrev_b32_e32 v214, 16, v215
	v_and_b32_e32 v215, 0xffff0000, v215
	s_mov_b64 exec, s[10:11]
	v_pk_add_f32 v[32:33], v[208:209], v[32:33]
	v_pk_add_f32 v[28:29], v[210:211], v[28:29]
	v_pk_add_f32 v[24:25], v[212:213], v[24:25]
	v_pk_add_f32 v[20:21], v[214:215], v[20:21]
	s_branch .LBB0_315
